# P6a tiles and the following P7a items taken from the workgroup's own XCD row range (flag set)
# speedup vs baseline: 1.0031x; 1.0003x over previous
; #define LAS __attribute__((address_space(3)))
; __device__ __forceinline__ unsigned pk2(float lo, float hi) { const f32x2c v = {lo, hi}; const bf16x2c b = __builtin_convertvector(v, bf16x2c); return __builtin_bit_cast(unsigned, b); }
; __device__ __forceinline__ float bflo(unsigned w) { return __uint_as_float(w << 16); }
; __device__ __forceinline__ float bfhi(unsigned w) { return __uint_as_float(w & 0xffff0000u); }
; __device__ __forceinline__ float fast_sigmoid(float x) { return __builtin_amdgcn_rcpf(1.f + __expf(-x)); }
; #define lane (lane_now())
; __device__ __forceinline__ f32x4 lerp4(const bf16_t* cur, const bf16_t* prv, bool first, const float* mu) {
;     const u32x2 a = *(const u32x2*)cur; u32x2 q = *(const u32x2*)prv; if (first) { q.x = 0u; q.y = 0u; }
;     const f32x4 m = *(const f32x4*)mu;
;     const f32x4 x = {bflo(a.x), bfhi(a.x), bflo(a.y), bfhi(a.y)}, y = {bflo(q.x), bfhi(q.x), bflo(q.y), bfhi(q.y)};
;     return x + (y - x) * m;
; }
; __device__ __forceinline__ void prep_rwkv_phase(const Params& p, LAS unsigned char* lds, int gw, int ngw, int wave, int lane) {
;     ...
;     const int item = gw + kit * ngw; const bool active = item < ntiles;
;     const int m0 = (active ? item : 0) * 16, b = m0 >> 13;
;     u32x4 wreg[4]; prep_w_load(p, 0, tid, wreg);
;     if (active) {
;         const int tk = lane >> 2, cq = lane & 3, m = m0 + tk; const bool first = (m & 8191) == 0;
;         const bf16_t* pr = PA + (size_t)m * NPA + 1536 + cq * 64; const bf16_t* pp = first ? pr : pr - NPA;
; #pragma unroll
;         for (int g8 = 0; g8 < 8; ++g8) {
;             const f32x4 x0 = lerp4(pr + g8 * 8, pp + g8 * 8, first, p.mu + 1536 + cq * 64 + g8 * 8);
;             const f32x4 x1 = lerp4(pr + g8 * 8 + 4, pp + g8 * 8 + 4, first, p.mu + 1536 + cq * 64 + g8 * 8 + 4);
;             float v[8] = {x0.x, x0.y, x0.z, x0.w, x1.x, x1.y, x1.z, x1.w};
; #pragma unroll
;             for (int e = 0; e < 8; ++e) { if (cq == 0) v[e] = 1.f - 2.f * __builtin_amdgcn_rcpf(__expf(2.f * v[e]) + 1.f); else if (cq >= 2) v[e] = fast_sigmoid(v[e]); }
;             u32x4 w; w.x = pk2(v[0], v[1]); w.y = pk2(v[2], v[3]); w.z = pk2(v[4], v[5]); w.w = pk2(v[6], v[7]);
;             *(LAS u32x4*)(act + tk * 264 + cq * 64 + g8 * 8) = w;
;         }
.LBB0_467:
	global_load_dwordx4 v[4:7], v[100:101], off
	global_load_dwordx4 v[8:11], v[102:103], off
	global_load_dwordx4 v[12:15], v[104:105], off
	global_load_dwordx4 v[16:19], v[106:107], off
	s_mul_i32 s6, s24, s84
	s_add_i32 s6, s6, s78
	v_readlane_b32 s100, v244, 61
	s_cmp_eq_u32 s100, 0
	s_cbranch_scc1 .Lxp_keep
	s_lshr_b32 s100, s78, 3
	s_and_b32 s101, s100, 7
	s_lshl_b32 s101, s101, 8
	s_and_b32 s100, s100, 0xfffffff8
	s_add_i32 s101, s101, s100
	s_and_b32 s100, s78, 7
	s_add_i32 s101, s101, s100
	s_sub_i32 s6, s6, s78
	s_add_i32 s6, s6, s101
.Lxp_keep:
	s_cmpk_lt_i32 s6, 0x800
	s_cselect_b64 s[20:21], -1, 0
	s_lshl_b32 s30, s6, 4
	s_cmpk_gt_i32 s6, 0x7ff
	s_cbranch_scc1 .LBB0_853
	s_waitcnt lgkmcnt(0)
	v_mov_b32_e32 v245, 0xbfb8aa3b
	v_mov_b32_e32 v246, 1.0
	v_mov_b32_e32 v247, 0
	v_mov_b32_e32 v2, 0x4038aa3b
	v_cmp_eq_u32_e32 vcc, 0, v207
	v_cmp_eq_u32_e64 s[98:99], 1, v207
	s_nop 1
	v_cndmask_b32_e32 v245, v245, v2, vcc
	v_cndmask_b32_e64 v246, v246, -2.0, vcc
	v_cndmask_b32_e64 v247, v247, 1.0, vcc
	v_add_u32_e32 v2, s30, v206
	v_mad_i64_i32 v[0:1], s[6:7], v2, s26, v[124:125]
	v_and_b32_e32 v2, 0x1fff, v2
	v_cmp_eq_u32_e32 vcc, 0, v2
	global_load_dwordx4 v[22:25], v[0:1], off offset:3072
	v_cmp_lt_i32_e64 s[6:7], 0, v207
	v_cndmask_b32_e64 v21, -1, 0, vcc
	v_cndmask_b32_e64 v20, v224, 0, vcc
	v_lshl_add_u64 v[20:21], v[0:1], 0, v[20:21]
	global_load_dwordx4 v[26:29], v[20:21], off offset:3072
	global_load_dwordx4 v[30:33], v[108:109], off
	global_load_dwordx4 v[34:37], v[108:109], off offset:16
	s_waitcnt vmcnt(3)
	v_lshlrev_b32_e32 v40, 16, v24
	v_and_b32_e32 v41, 0xffff0000, v24
	v_lshlrev_b32_e32 v42, 16, v25
	v_and_b32_e32 v43, 0xffff0000, v25
	s_waitcnt vmcnt(2)
	v_cndmask_b32_e64 v2, v27, 0, vcc
	v_cndmask_b32_e64 v24, v26, 0, vcc
	v_cndmask_b32_e64 v25, v29, 0, vcc
	v_cndmask_b32_e64 v26, v28, 0, vcc
	v_lshlrev_b32_e32 v38, 16, v22
	v_and_b32_e32 v39, 0xffff0000, v22
	v_lshlrev_b32_e32 v22, 16, v23
	v_and_b32_e32 v23, 0xffff0000, v23
	v_lshlrev_b32_e32 v27, 16, v24
	v_and_b32_e32 v24, 0xffff0000, v24
	v_lshlrev_b32_e32 v28, 16, v2
	v_and_b32_e32 v2, 0xffff0000, v2
	v_lshlrev_b32_e32 v44, 16, v26
	v_and_b32_e32 v29, 0xffff0000, v26
	v_lshlrev_b32_e32 v46, 16, v25
	v_and_b32_e32 v45, 0xffff0000, v25
	v_sub_f32_e32 v25, v24, v39
	v_sub_f32_e32 v24, v27, v38
	v_sub_f32_e32 v27, v2, v23
	v_sub_f32_e32 v26, v28, v22
	v_sub_f32_e32 v29, v29, v41
	v_sub_f32_e32 v28, v44, v40
	v_sub_f32_e32 v45, v45, v43
	v_sub_f32_e32 v44, v46, v42
	s_waitcnt vmcnt(1)
	v_pk_fma_f32 v[22:23], v[32:33], v[26:27], v[22:23]
	v_pk_fma_f32 v[24:25], v[30:31], v[24:25], v[38:39]
	s_waitcnt vmcnt(0)
	v_pk_fma_f32 v[26:27], v[36:37], v[44:45], v[42:43]
	v_pk_fma_f32 v[28:29], v[34:35], v[28:29], v[40:41]
	v_mul_f32_e32 v240, v245, v24
	v_mul_f32_e32 v241, v245, v25
	v_mul_f32_e32 v242, v245, v22
	v_mul_f32_e32 v243, v245, v23
	v_exp_f32_e32 v240, v240
	v_exp_f32_e32 v241, v241
	v_exp_f32_e32 v242, v242
	v_exp_f32_e32 v243, v243
	v_add_f32_e32 v240, 1.0, v240
	v_add_f32_e32 v241, 1.0, v241
	v_add_f32_e32 v242, 1.0, v242
	v_add_f32_e32 v243, 1.0, v243
	v_rcp_f32_e32 v240, v240
	v_rcp_f32_e32 v241, v241
	v_rcp_f32_e32 v242, v242
	v_rcp_f32_e32 v243, v243
	v_fma_f32 v240, v240, v246, v247
	v_fma_f32 v241, v241, v246, v247
	v_fma_f32 v242, v242, v246, v247
	v_fma_f32 v243, v243, v246, v247
	v_cndmask_b32_e64 v24, v240, v24, s[98:99]
	v_cndmask_b32_e64 v25, v241, v25, s[98:99]
	v_cndmask_b32_e64 v22, v242, v22, s[98:99]
	v_cndmask_b32_e64 v23, v243, v23, s[98:99]
	v_mul_f32_e32 v240, v245, v28
	v_mul_f32_e32 v241, v245, v29
	v_mul_f32_e32 v242, v245, v26
	v_mul_f32_e32 v243, v245, v27
	v_exp_f32_e32 v240, v240
	v_exp_f32_e32 v241, v241
	v_exp_f32_e32 v242, v242
	v_exp_f32_e32 v243, v243
	v_add_f32_e32 v240, 1.0, v240
	v_add_f32_e32 v241, 1.0, v241
	v_add_f32_e32 v242, 1.0, v242
	v_add_f32_e32 v243, 1.0, v243
	v_rcp_f32_e32 v240, v240
	v_rcp_f32_e32 v241, v241
	v_rcp_f32_e32 v242, v242
	v_rcp_f32_e32 v243, v243
	v_fma_f32 v240, v240, v246, v247
	v_fma_f32 v241, v241, v246, v247
	v_fma_f32 v242, v242, v246, v247
	v_fma_f32 v243, v243, v246, v247
	v_cndmask_b32_e64 v28, v240, v28, s[98:99]
	v_cndmask_b32_e64 v29, v241, v29, s[98:99]
	v_cndmask_b32_e64 v26, v242, v26, s[98:99]
	v_cndmask_b32_e64 v27, v243, v27, s[98:99]
	v_cvt_pk_bf16_f32 v30, v24, v25
	v_cvt_pk_bf16_f32 v31, v22, v23
	v_cvt_pk_bf16_f32 v32, v28, v29
	v_cvt_pk_bf16_f32 v33, v26, v27
	ds_write_b128 v208, v[30:33]
	global_load_dwordx4 v[22:25], v[20:21], off offset:3088
	global_load_dwordx4 v[26:29], v[0:1], off offset:3088
	global_load_dwordx4 v[30:33], v[110:111], off
	global_load_dwordx4 v[34:37], v[110:111], off offset:16
	v_cmp_lt_i32_e64 s[6:7], 0, v207
	s_waitcnt vmcnt(3)
	v_cndmask_b32_e64 v2, v23, 0, vcc
	v_cndmask_b32_e64 v42, v22, 0, vcc
	v_cndmask_b32_e64 v25, v25, 0, vcc
	v_cndmask_b32_e64 v24, v24, 0, vcc
	s_waitcnt vmcnt(2)
	v_lshlrev_b32_e32 v38, 16, v26
	v_and_b32_e32 v39, 0xffff0000, v26
	v_lshlrev_b32_e32 v22, 16, v27
	v_and_b32_e32 v23, 0xffff0000, v27
	v_lshlrev_b32_e32 v40, 16, v28
	v_and_b32_e32 v41, 0xffff0000, v28
	v_lshlrev_b32_e32 v26, 16, v29
	v_and_b32_e32 v27, 0xffff0000, v29
	v_lshlrev_b32_e32 v28, 16, v42
	v_and_b32_e32 v29, 0xffff0000, v42
	v_lshlrev_b32_e32 v42, 16, v2
	v_and_b32_e32 v2, 0xffff0000, v2
	v_lshlrev_b32_e32 v44, 16, v24
	v_and_b32_e32 v43, 0xffff0000, v24
	v_lshlrev_b32_e32 v46, 16, v25
	v_and_b32_e32 v45, 0xffff0000, v25
	v_sub_f32_e32 v25, v29, v39
	v_sub_f32_e32 v24, v28, v38
	v_sub_f32_e32 v29, v2, v23
	v_sub_f32_e32 v28, v42, v22
	v_sub_f32_e32 v43, v43, v41
	v_sub_f32_e32 v42, v44, v40
	v_sub_f32_e32 v45, v45, v27
	v_sub_f32_e32 v44, v46, v26
	s_waitcnt vmcnt(1)
; #define LAS __attribute__((address_space(3)))
; __device__ __forceinline__ unsigned pk2(float lo, float hi) { const f32x2c v = {lo, hi}; const bf16x2c b = __builtin_convertvector(v, bf16x2c); return __builtin_bit_cast(unsigned, b); }
; __device__ __forceinline__ float bflo(unsigned w) { return __uint_as_float(w << 16); }
; __device__ __forceinline__ float bfhi(unsigned w) { return __uint_as_float(w & 0xffff0000u); }
; __device__ __forceinline__ float fast_sigmoid(float x) { return __builtin_amdgcn_rcpf(1.f + __expf(-x)); }
; __device__ __forceinline__ f32x4 lerp4(const bf16_t* cur, const bf16_t* prv, bool first, const float* mu) {
;     const u32x2 a = *(const u32x2*)cur; u32x2 q = *(const u32x2*)prv; if (first) { q.x = 0u; q.y = 0u; }
;     const f32x4 m = *(const f32x4*)mu;
;     const f32x4 x = {bflo(a.x), bfhi(a.x), bflo(a.y), bfhi(a.y)}, y = {bflo(q.x), bfhi(q.x), bflo(q.y), bfhi(q.y)};
;     return x + (y - x) * m;
; }
; __device__ __forceinline__ void prep_rwkv_phase(const Params& p, LAS unsigned char* lds, int gw, int ngw, int wave, int lane) {
;     ...
;         for (int g8 = 0; g8 < 8; ++g8) {
;             const f32x4 x0 = lerp4(pr + g8 * 8, pp + g8 * 8, first, p.mu + 1536 + cq * 64 + g8 * 8);
;             const f32x4 x1 = lerp4(pr + g8 * 8 + 4, pp + g8 * 8 + 4, first, p.mu + 1536 + cq * 64 + g8 * 8 + 4);
;             float v[8] = {x0.x, x0.y, x0.z, x0.w, x1.x, x1.y, x1.z, x1.w};
; #pragma unroll
;             for (int e = 0; e < 8; ++e) { if (cq == 0) v[e] = 1.f - 2.f * __builtin_amdgcn_rcpf(__expf(2.f * v[e]) + 1.f); else if (cq >= 2) v[e] = fast_sigmoid(v[e]); }
;             u32x4 w; w.x = pk2(v[0], v[1]); w.y = pk2(v[2], v[3]); w.z = pk2(v[4], v[5]); w.w = pk2(v[6], v[7]);
;             *(LAS u32x4*)(act + tk * 264 + cq * 64 + g8 * 8) = w;
;         }
	v_pk_fma_f32 v[22:23], v[32:33], v[28:29], v[22:23]
	v_pk_fma_f32 v[24:25], v[30:31], v[24:25], v[38:39]
	s_waitcnt vmcnt(0)
	v_pk_fma_f32 v[26:27], v[36:37], v[44:45], v[26:27]
	v_pk_fma_f32 v[28:29], v[34:35], v[42:43], v[40:41]
	v_mul_f32_e32 v240, v245, v24
	v_mul_f32_e32 v241, v245, v25
	v_mul_f32_e32 v242, v245, v22
	v_mul_f32_e32 v243, v245, v23
	v_exp_f32_e32 v240, v240
	v_exp_f32_e32 v241, v241
	v_exp_f32_e32 v242, v242
	v_exp_f32_e32 v243, v243
	v_add_f32_e32 v240, 1.0, v240
	v_add_f32_e32 v241, 1.0, v241
	v_add_f32_e32 v242, 1.0, v242
	v_add_f32_e32 v243, 1.0, v243
	v_rcp_f32_e32 v240, v240
	v_rcp_f32_e32 v241, v241
	v_rcp_f32_e32 v242, v242
	v_rcp_f32_e32 v243, v243
	v_fma_f32 v240, v240, v246, v247
	v_fma_f32 v241, v241, v246, v247
	v_fma_f32 v242, v242, v246, v247
	v_fma_f32 v243, v243, v246, v247
	v_cndmask_b32_e64 v24, v240, v24, s[98:99]
	v_cndmask_b32_e64 v25, v241, v25, s[98:99]
	v_cndmask_b32_e64 v22, v242, v22, s[98:99]
	v_cndmask_b32_e64 v23, v243, v23, s[98:99]
	v_mul_f32_e32 v240, v245, v28
	v_mul_f32_e32 v241, v245, v29
	v_mul_f32_e32 v242, v245, v26
	v_mul_f32_e32 v243, v245, v27
	v_exp_f32_e32 v240, v240
	v_exp_f32_e32 v241, v241
	v_exp_f32_e32 v242, v242
	v_exp_f32_e32 v243, v243
	v_add_f32_e32 v240, 1.0, v240
	v_add_f32_e32 v241, 1.0, v241
	v_add_f32_e32 v242, 1.0, v242
	v_add_f32_e32 v243, 1.0, v243
	v_rcp_f32_e32 v240, v240
	v_rcp_f32_e32 v241, v241
	v_rcp_f32_e32 v242, v242
	v_rcp_f32_e32 v243, v243
	v_fma_f32 v240, v240, v246, v247
	v_fma_f32 v241, v241, v246, v247
	v_fma_f32 v242, v242, v246, v247
	v_fma_f32 v243, v243, v246, v247
	v_cndmask_b32_e64 v28, v240, v28, s[98:99]
	v_cndmask_b32_e64 v29, v241, v29, s[98:99]
	v_cndmask_b32_e64 v26, v242, v26, s[98:99]
	v_cndmask_b32_e64 v27, v243, v27, s[98:99]
	v_cvt_pk_bf16_f32 v30, v24, v25
	v_cvt_pk_bf16_f32 v31, v22, v23
	v_cvt_pk_bf16_f32 v32, v28, v29
	v_cvt_pk_bf16_f32 v33, v26, v27
	ds_write_b128 v208, v[30:33] offset:16
	global_load_dwordx4 v[22:25], v[20:21], off offset:3104
	global_load_dwordx4 v[26:29], v[0:1], off offset:3104
	global_load_dwordx4 v[30:33], v[112:113], off
	global_load_dwordx4 v[34:37], v[112:113], off offset:16
	v_cmp_lt_i32_e64 s[6:7], 0, v207
	s_waitcnt vmcnt(3)
	v_cndmask_b32_e64 v2, v23, 0, vcc
	v_cndmask_b32_e64 v42, v22, 0, vcc
	v_cndmask_b32_e64 v25, v25, 0, vcc
	v_cndmask_b32_e64 v24, v24, 0, vcc
	s_waitcnt vmcnt(2)
	v_lshlrev_b32_e32 v38, 16, v26
	v_and_b32_e32 v39, 0xffff0000, v26
	v_lshlrev_b32_e32 v22, 16, v27
	v_and_b32_e32 v23, 0xffff0000, v27
	v_lshlrev_b32_e32 v40, 16, v28
	v_and_b32_e32 v41, 0xffff0000, v28
	v_lshlrev_b32_e32 v26, 16, v29
	v_and_b32_e32 v27, 0xffff0000, v29
	v_lshlrev_b32_e32 v28, 16, v42
	v_and_b32_e32 v29, 0xffff0000, v42
	v_lshlrev_b32_e32 v42, 16, v2
	v_and_b32_e32 v2, 0xffff0000, v2
	v_lshlrev_b32_e32 v44, 16, v24
	v_and_b32_e32 v43, 0xffff0000, v24
	v_lshlrev_b32_e32 v46, 16, v25
	v_and_b32_e32 v45, 0xffff0000, v25
	v_sub_f32_e32 v25, v29, v39
	v_sub_f32_e32 v24, v28, v38
	v_sub_f32_e32 v29, v2, v23
	v_sub_f32_e32 v28, v42, v22
	v_sub_f32_e32 v43, v43, v41
	v_sub_f32_e32 v42, v44, v40
	v_sub_f32_e32 v45, v45, v27
	v_sub_f32_e32 v44, v46, v26
	s_waitcnt vmcnt(1)
	v_pk_fma_f32 v[22:23], v[32:33], v[28:29], v[22:23]
	v_pk_fma_f32 v[24:25], v[30:31], v[24:25], v[38:39]
	s_waitcnt vmcnt(0)
	v_pk_fma_f32 v[26:27], v[36:37], v[44:45], v[26:27]
	v_pk_fma_f32 v[28:29], v[34:35], v[42:43], v[40:41]
	v_mul_f32_e32 v240, v245, v24
	v_mul_f32_e32 v241, v245, v25
	v_mul_f32_e32 v242, v245, v22
	v_mul_f32_e32 v243, v245, v23
	v_exp_f32_e32 v240, v240
	v_exp_f32_e32 v241, v241
	v_exp_f32_e32 v242, v242
	v_exp_f32_e32 v243, v243
	v_add_f32_e32 v240, 1.0, v240
	v_add_f32_e32 v241, 1.0, v241
	v_add_f32_e32 v242, 1.0, v242
	v_add_f32_e32 v243, 1.0, v243
	v_rcp_f32_e32 v240, v240
	v_rcp_f32_e32 v241, v241
	v_rcp_f32_e32 v242, v242
	v_rcp_f32_e32 v243, v243
	v_fma_f32 v240, v240, v246, v247
	v_fma_f32 v241, v241, v246, v247
	v_fma_f32 v242, v242, v246, v247
	v_fma_f32 v243, v243, v246, v247
	v_cndmask_b32_e64 v24, v240, v24, s[98:99]
	v_cndmask_b32_e64 v25, v241, v25, s[98:99]
	v_cndmask_b32_e64 v22, v242, v22, s[98:99]
	v_cndmask_b32_e64 v23, v243, v23, s[98:99]
	v_mul_f32_e32 v240, v245, v28
	v_mul_f32_e32 v241, v245, v29
	v_mul_f32_e32 v242, v245, v26
	v_mul_f32_e32 v243, v245, v27
	v_exp_f32_e32 v240, v240
	v_exp_f32_e32 v241, v241
	v_exp_f32_e32 v242, v242
	v_exp_f32_e32 v243, v243
	v_add_f32_e32 v240, 1.0, v240
	v_add_f32_e32 v241, 1.0, v241
	v_add_f32_e32 v242, 1.0, v242
	v_add_f32_e32 v243, 1.0, v243
	v_rcp_f32_e32 v240, v240
	v_rcp_f32_e32 v241, v241
	v_rcp_f32_e32 v242, v242
	v_rcp_f32_e32 v243, v243
	v_fma_f32 v240, v240, v246, v247
	v_fma_f32 v241, v241, v246, v247
	v_fma_f32 v242, v242, v246, v247
	v_fma_f32 v243, v243, v246, v247
	v_cndmask_b32_e64 v28, v240, v28, s[98:99]
	v_cndmask_b32_e64 v29, v241, v29, s[98:99]
	v_cndmask_b32_e64 v26, v242, v26, s[98:99]
	v_cndmask_b32_e64 v27, v243, v27, s[98:99]
	v_cvt_pk_bf16_f32 v30, v24, v25
	v_cvt_pk_bf16_f32 v31, v22, v23
	v_cvt_pk_bf16_f32 v32, v28, v29
	v_cvt_pk_bf16_f32 v33, v26, v27
	ds_write_b128 v208, v[30:33] offset:32
	global_load_dwordx4 v[22:25], v[20:21], off offset:3120
	global_load_dwordx4 v[26:29], v[0:1], off offset:3120
	global_load_dwordx4 v[30:33], v[114:115], off
	global_load_dwordx4 v[34:37], v[114:115], off offset:16
	v_cmp_lt_i32_e64 s[6:7], 0, v207
	s_waitcnt vmcnt(3)
	v_cndmask_b32_e64 v2, v23, 0, vcc
	v_cndmask_b32_e64 v42, v22, 0, vcc
	v_cndmask_b32_e64 v25, v25, 0, vcc
	v_cndmask_b32_e64 v24, v24, 0, vcc
	s_waitcnt vmcnt(2)
; #define LAS __attribute__((address_space(3)))
; __device__ __forceinline__ unsigned pk2(float lo, float hi) { const f32x2c v = {lo, hi}; const bf16x2c b = __builtin_convertvector(v, bf16x2c); return __builtin_bit_cast(unsigned, b); }
; __device__ __forceinline__ float bflo(unsigned w) { return __uint_as_float(w << 16); }
; __device__ __forceinline__ float bfhi(unsigned w) { return __uint_as_float(w & 0xffff0000u); }
; __device__ __forceinline__ float fast_sigmoid(float x) { return __builtin_amdgcn_rcpf(1.f + __expf(-x)); }
; __device__ __forceinline__ f32x4 lerp4(const bf16_t* cur, const bf16_t* prv, bool first, const float* mu) {
;     const u32x2 a = *(const u32x2*)cur; u32x2 q = *(const u32x2*)prv; if (first) { q.x = 0u; q.y = 0u; }
;     const f32x4 m = *(const f32x4*)mu;
;     const f32x4 x = {bflo(a.x), bfhi(a.x), bflo(a.y), bfhi(a.y)}, y = {bflo(q.x), bfhi(q.x), bflo(q.y), bfhi(q.y)};
;     return x + (y - x) * m;
; }
; __device__ __forceinline__ void prep_rwkv_phase(const Params& p, LAS unsigned char* lds, int gw, int ngw, int wave, int lane) {
;     ...
;         for (int g8 = 0; g8 < 8; ++g8) {
;             const f32x4 x0 = lerp4(pr + g8 * 8, pp + g8 * 8, first, p.mu + 1536 + cq * 64 + g8 * 8);
;             const f32x4 x1 = lerp4(pr + g8 * 8 + 4, pp + g8 * 8 + 4, first, p.mu + 1536 + cq * 64 + g8 * 8 + 4);
;             float v[8] = {x0.x, x0.y, x0.z, x0.w, x1.x, x1.y, x1.z, x1.w};
; #pragma unroll
;             for (int e = 0; e < 8; ++e) { if (cq == 0) v[e] = 1.f - 2.f * __builtin_amdgcn_rcpf(__expf(2.f * v[e]) + 1.f); else if (cq >= 2) v[e] = fast_sigmoid(v[e]); }
;             u32x4 w; w.x = pk2(v[0], v[1]); w.y = pk2(v[2], v[3]); w.z = pk2(v[4], v[5]); w.w = pk2(v[6], v[7]);
;             *(LAS u32x4*)(act + tk * 264 + cq * 64 + g8 * 8) = w;
;         }
	v_lshlrev_b32_e32 v38, 16, v26
	v_and_b32_e32 v39, 0xffff0000, v26
	v_lshlrev_b32_e32 v22, 16, v27
	v_and_b32_e32 v23, 0xffff0000, v27
	v_lshlrev_b32_e32 v40, 16, v28
	v_and_b32_e32 v41, 0xffff0000, v28
	v_lshlrev_b32_e32 v26, 16, v29
	v_and_b32_e32 v27, 0xffff0000, v29
	v_lshlrev_b32_e32 v28, 16, v42
	v_and_b32_e32 v29, 0xffff0000, v42
	v_lshlrev_b32_e32 v42, 16, v2
	v_and_b32_e32 v2, 0xffff0000, v2
	v_lshlrev_b32_e32 v44, 16, v24
	v_and_b32_e32 v43, 0xffff0000, v24
	v_lshlrev_b32_e32 v46, 16, v25
	v_and_b32_e32 v45, 0xffff0000, v25
	v_sub_f32_e32 v25, v29, v39
	v_sub_f32_e32 v24, v28, v38
	v_sub_f32_e32 v29, v2, v23
	v_sub_f32_e32 v28, v42, v22
	v_sub_f32_e32 v43, v43, v41
	v_sub_f32_e32 v42, v44, v40
	v_sub_f32_e32 v45, v45, v27
	v_sub_f32_e32 v44, v46, v26
	s_waitcnt vmcnt(1)
	v_pk_fma_f32 v[22:23], v[32:33], v[28:29], v[22:23]
	v_pk_fma_f32 v[24:25], v[30:31], v[24:25], v[38:39]
	s_waitcnt vmcnt(0)
	v_pk_fma_f32 v[26:27], v[36:37], v[44:45], v[26:27]
	v_pk_fma_f32 v[28:29], v[34:35], v[42:43], v[40:41]
	v_mul_f32_e32 v240, v245, v24
	v_mul_f32_e32 v241, v245, v25
	v_mul_f32_e32 v242, v245, v22
	v_mul_f32_e32 v243, v245, v23
	v_exp_f32_e32 v240, v240
	v_exp_f32_e32 v241, v241
	v_exp_f32_e32 v242, v242
	v_exp_f32_e32 v243, v243
	v_add_f32_e32 v240, 1.0, v240
	v_add_f32_e32 v241, 1.0, v241
	v_add_f32_e32 v242, 1.0, v242
	v_add_f32_e32 v243, 1.0, v243
	v_rcp_f32_e32 v240, v240
	v_rcp_f32_e32 v241, v241
	v_rcp_f32_e32 v242, v242
	v_rcp_f32_e32 v243, v243
	v_fma_f32 v240, v240, v246, v247
	v_fma_f32 v241, v241, v246, v247
	v_fma_f32 v242, v242, v246, v247
	v_fma_f32 v243, v243, v246, v247
	v_cndmask_b32_e64 v24, v240, v24, s[98:99]
	v_cndmask_b32_e64 v25, v241, v25, s[98:99]
	v_cndmask_b32_e64 v22, v242, v22, s[98:99]
	v_cndmask_b32_e64 v23, v243, v23, s[98:99]
	v_mul_f32_e32 v240, v245, v28
	v_mul_f32_e32 v241, v245, v29
	v_mul_f32_e32 v242, v245, v26
	v_mul_f32_e32 v243, v245, v27
	v_exp_f32_e32 v240, v240
	v_exp_f32_e32 v241, v241
	v_exp_f32_e32 v242, v242
	v_exp_f32_e32 v243, v243
	v_add_f32_e32 v240, 1.0, v240
	v_add_f32_e32 v241, 1.0, v241
	v_add_f32_e32 v242, 1.0, v242
	v_add_f32_e32 v243, 1.0, v243
	v_rcp_f32_e32 v240, v240
	v_rcp_f32_e32 v241, v241
	v_rcp_f32_e32 v242, v242
	v_rcp_f32_e32 v243, v243
	v_fma_f32 v240, v240, v246, v247
	v_fma_f32 v241, v241, v246, v247
	v_fma_f32 v242, v242, v246, v247
	v_fma_f32 v243, v243, v246, v247
	v_cndmask_b32_e64 v28, v240, v28, s[98:99]
	v_cndmask_b32_e64 v29, v241, v29, s[98:99]
	v_cndmask_b32_e64 v26, v242, v26, s[98:99]
	v_cndmask_b32_e64 v27, v243, v27, s[98:99]
	v_cvt_pk_bf16_f32 v30, v24, v25
	v_cvt_pk_bf16_f32 v31, v22, v23
	v_cvt_pk_bf16_f32 v32, v28, v29
	v_cvt_pk_bf16_f32 v33, v26, v27
	ds_write_b128 v208, v[30:33] offset:48
	global_load_dwordx4 v[22:25], v[20:21], off offset:3136
	global_load_dwordx4 v[26:29], v[0:1], off offset:3136
	global_load_dwordx4 v[30:33], v[116:117], off
	global_load_dwordx4 v[34:37], v[116:117], off offset:16
	v_cmp_lt_i32_e64 s[6:7], 0, v207
	s_waitcnt vmcnt(3)
	v_cndmask_b32_e64 v2, v23, 0, vcc
	v_cndmask_b32_e64 v42, v22, 0, vcc
	v_cndmask_b32_e64 v25, v25, 0, vcc
	v_cndmask_b32_e64 v24, v24, 0, vcc
	s_waitcnt vmcnt(2)
	v_lshlrev_b32_e32 v38, 16, v26
	v_and_b32_e32 v39, 0xffff0000, v26
	v_lshlrev_b32_e32 v22, 16, v27
	v_and_b32_e32 v23, 0xffff0000, v27
	v_lshlrev_b32_e32 v40, 16, v28
	v_and_b32_e32 v41, 0xffff0000, v28
	v_lshlrev_b32_e32 v26, 16, v29
	v_and_b32_e32 v27, 0xffff0000, v29
	v_lshlrev_b32_e32 v28, 16, v42
	v_and_b32_e32 v29, 0xffff0000, v42
	v_lshlrev_b32_e32 v42, 16, v2
	v_and_b32_e32 v2, 0xffff0000, v2
	v_lshlrev_b32_e32 v44, 16, v24
	v_and_b32_e32 v43, 0xffff0000, v24
	v_lshlrev_b32_e32 v46, 16, v25
	v_and_b32_e32 v45, 0xffff0000, v25
	v_sub_f32_e32 v25, v29, v39
	v_sub_f32_e32 v24, v28, v38
	v_sub_f32_e32 v29, v2, v23
	v_sub_f32_e32 v28, v42, v22
	v_sub_f32_e32 v43, v43, v41
	v_sub_f32_e32 v42, v44, v40
	v_sub_f32_e32 v45, v45, v27
	v_sub_f32_e32 v44, v46, v26
	s_waitcnt vmcnt(1)
	v_pk_fma_f32 v[22:23], v[32:33], v[28:29], v[22:23]
	v_pk_fma_f32 v[24:25], v[30:31], v[24:25], v[38:39]
	s_waitcnt vmcnt(0)
	v_pk_fma_f32 v[26:27], v[36:37], v[44:45], v[26:27]
	v_pk_fma_f32 v[28:29], v[34:35], v[42:43], v[40:41]
	v_mul_f32_e32 v240, v245, v24
	v_mul_f32_e32 v241, v245, v25
	v_mul_f32_e32 v242, v245, v22
	v_mul_f32_e32 v243, v245, v23
	v_exp_f32_e32 v240, v240
	v_exp_f32_e32 v241, v241
	v_exp_f32_e32 v242, v242
	v_exp_f32_e32 v243, v243
	v_add_f32_e32 v240, 1.0, v240
	v_add_f32_e32 v241, 1.0, v241
	v_add_f32_e32 v242, 1.0, v242
	v_add_f32_e32 v243, 1.0, v243
	v_rcp_f32_e32 v240, v240
	v_rcp_f32_e32 v241, v241
	v_rcp_f32_e32 v242, v242
	v_rcp_f32_e32 v243, v243
	v_fma_f32 v240, v240, v246, v247
	v_fma_f32 v241, v241, v246, v247
	v_fma_f32 v242, v242, v246, v247
	v_fma_f32 v243, v243, v246, v247
	v_cndmask_b32_e64 v24, v240, v24, s[98:99]
	v_cndmask_b32_e64 v25, v241, v25, s[98:99]
	v_cndmask_b32_e64 v22, v242, v22, s[98:99]
	v_cndmask_b32_e64 v23, v243, v23, s[98:99]
	v_mul_f32_e32 v240, v245, v28
	v_mul_f32_e32 v241, v245, v29
	v_mul_f32_e32 v242, v245, v26
	v_mul_f32_e32 v243, v245, v27
	v_exp_f32_e32 v240, v240
	v_exp_f32_e32 v241, v241
	v_exp_f32_e32 v242, v242
	v_exp_f32_e32 v243, v243
	v_add_f32_e32 v240, 1.0, v240
	v_add_f32_e32 v241, 1.0, v241
	v_add_f32_e32 v242, 1.0, v242
	v_add_f32_e32 v243, 1.0, v243
	v_rcp_f32_e32 v240, v240
	v_rcp_f32_e32 v241, v241
	v_rcp_f32_e32 v242, v242
	v_rcp_f32_e32 v243, v243
	v_fma_f32 v240, v240, v246, v247
	v_fma_f32 v241, v241, v246, v247
	v_fma_f32 v242, v242, v246, v247
	v_fma_f32 v243, v243, v246, v247
	v_cndmask_b32_e64 v28, v240, v28, s[98:99]
	v_cndmask_b32_e64 v29, v241, v29, s[98:99]
	v_cndmask_b32_e64 v26, v242, v26, s[98:99]
	v_cndmask_b32_e64 v27, v243, v27, s[98:99]
	v_cvt_pk_bf16_f32 v30, v24, v25
	v_cvt_pk_bf16_f32 v31, v22, v23
	v_cvt_pk_bf16_f32 v32, v28, v29
	v_cvt_pk_bf16_f32 v33, v26, v27
	ds_write_b128 v208, v[30:33] offset:64
	global_load_dwordx4 v[22:25], v[20:21], off offset:3152
	global_load_dwordx4 v[26:29], v[0:1], off offset:3152
	global_load_dwordx4 v[30:33], v[118:119], off
	global_load_dwordx4 v[34:37], v[118:119], off offset:16
	v_cmp_lt_i32_e64 s[6:7], 0, v207
	s_waitcnt vmcnt(3)
; #define LAS __attribute__((address_space(3)))
; __device__ __forceinline__ unsigned pk2(float lo, float hi) { const f32x2c v = {lo, hi}; const bf16x2c b = __builtin_convertvector(v, bf16x2c); return __builtin_bit_cast(unsigned, b); }
; __device__ __forceinline__ float bflo(unsigned w) { return __uint_as_float(w << 16); }
; __device__ __forceinline__ float bfhi(unsigned w) { return __uint_as_float(w & 0xffff0000u); }
; __device__ __forceinline__ float fast_sigmoid(float x) { return __builtin_amdgcn_rcpf(1.f + __expf(-x)); }
; __device__ __forceinline__ f32x4 lerp4(const bf16_t* cur, const bf16_t* prv, bool first, const float* mu) {
;     const u32x2 a = *(const u32x2*)cur; u32x2 q = *(const u32x2*)prv; if (first) { q.x = 0u; q.y = 0u; }
;     const f32x4 m = *(const f32x4*)mu;
;     const f32x4 x = {bflo(a.x), bfhi(a.x), bflo(a.y), bfhi(a.y)}, y = {bflo(q.x), bfhi(q.x), bflo(q.y), bfhi(q.y)};
;     return x + (y - x) * m;
; }
; __device__ __forceinline__ void prep_rwkv_phase(const Params& p, LAS unsigned char* lds, int gw, int ngw, int wave, int lane) {
;     ...
;         for (int g8 = 0; g8 < 8; ++g8) {
;             const f32x4 x0 = lerp4(pr + g8 * 8, pp + g8 * 8, first, p.mu + 1536 + cq * 64 + g8 * 8);
;             const f32x4 x1 = lerp4(pr + g8 * 8 + 4, pp + g8 * 8 + 4, first, p.mu + 1536 + cq * 64 + g8 * 8 + 4);
;             float v[8] = {x0.x, x0.y, x0.z, x0.w, x1.x, x1.y, x1.z, x1.w};
; #pragma unroll
;             for (int e = 0; e < 8; ++e) { if (cq == 0) v[e] = 1.f - 2.f * __builtin_amdgcn_rcpf(__expf(2.f * v[e]) + 1.f); else if (cq >= 2) v[e] = fast_sigmoid(v[e]); }
;             u32x4 w; w.x = pk2(v[0], v[1]); w.y = pk2(v[2], v[3]); w.z = pk2(v[4], v[5]); w.w = pk2(v[6], v[7]);
;             *(LAS u32x4*)(act + tk * 264 + cq * 64 + g8 * 8) = w;
;         }
	v_cndmask_b32_e64 v2, v23, 0, vcc
	v_cndmask_b32_e64 v42, v22, 0, vcc
	v_cndmask_b32_e64 v25, v25, 0, vcc
	v_cndmask_b32_e64 v24, v24, 0, vcc
	s_waitcnt vmcnt(2)
	v_lshlrev_b32_e32 v38, 16, v26
	v_and_b32_e32 v39, 0xffff0000, v26
	v_lshlrev_b32_e32 v22, 16, v27
	v_and_b32_e32 v23, 0xffff0000, v27
	v_lshlrev_b32_e32 v40, 16, v28
	v_and_b32_e32 v41, 0xffff0000, v28
	v_lshlrev_b32_e32 v26, 16, v29
	v_and_b32_e32 v27, 0xffff0000, v29
	v_lshlrev_b32_e32 v28, 16, v42
	v_and_b32_e32 v29, 0xffff0000, v42
	v_lshlrev_b32_e32 v42, 16, v2
	v_and_b32_e32 v2, 0xffff0000, v2
	v_lshlrev_b32_e32 v44, 16, v24
	v_and_b32_e32 v43, 0xffff0000, v24
	v_lshlrev_b32_e32 v46, 16, v25
	v_and_b32_e32 v45, 0xffff0000, v25
	v_sub_f32_e32 v25, v29, v39
	v_sub_f32_e32 v24, v28, v38
	v_sub_f32_e32 v29, v2, v23
	v_sub_f32_e32 v28, v42, v22
	v_sub_f32_e32 v43, v43, v41
	v_sub_f32_e32 v42, v44, v40
	v_sub_f32_e32 v45, v45, v27
	v_sub_f32_e32 v44, v46, v26
	s_waitcnt vmcnt(1)
	v_pk_fma_f32 v[22:23], v[32:33], v[28:29], v[22:23]
	v_pk_fma_f32 v[24:25], v[30:31], v[24:25], v[38:39]
	s_waitcnt vmcnt(0)
	v_pk_fma_f32 v[26:27], v[36:37], v[44:45], v[26:27]
	v_pk_fma_f32 v[28:29], v[34:35], v[42:43], v[40:41]
	v_mul_f32_e32 v240, v245, v24
	v_mul_f32_e32 v241, v245, v25
	v_mul_f32_e32 v242, v245, v22
	v_mul_f32_e32 v243, v245, v23
	v_exp_f32_e32 v240, v240
	v_exp_f32_e32 v241, v241
	v_exp_f32_e32 v242, v242
	v_exp_f32_e32 v243, v243
	v_add_f32_e32 v240, 1.0, v240
	v_add_f32_e32 v241, 1.0, v241
	v_add_f32_e32 v242, 1.0, v242
	v_add_f32_e32 v243, 1.0, v243
	v_rcp_f32_e32 v240, v240
	v_rcp_f32_e32 v241, v241
	v_rcp_f32_e32 v242, v242
	v_rcp_f32_e32 v243, v243
	v_fma_f32 v240, v240, v246, v247
	v_fma_f32 v241, v241, v246, v247
	v_fma_f32 v242, v242, v246, v247
	v_fma_f32 v243, v243, v246, v247
	v_cndmask_b32_e64 v24, v240, v24, s[98:99]
	v_cndmask_b32_e64 v25, v241, v25, s[98:99]
	v_cndmask_b32_e64 v22, v242, v22, s[98:99]
	v_cndmask_b32_e64 v23, v243, v23, s[98:99]
	v_mul_f32_e32 v240, v245, v28
	v_mul_f32_e32 v241, v245, v29
	v_mul_f32_e32 v242, v245, v26
	v_mul_f32_e32 v243, v245, v27
	v_exp_f32_e32 v240, v240
	v_exp_f32_e32 v241, v241
	v_exp_f32_e32 v242, v242
	v_exp_f32_e32 v243, v243
	v_add_f32_e32 v240, 1.0, v240
	v_add_f32_e32 v241, 1.0, v241
	v_add_f32_e32 v242, 1.0, v242
	v_add_f32_e32 v243, 1.0, v243
	v_rcp_f32_e32 v240, v240
	v_rcp_f32_e32 v241, v241
	v_rcp_f32_e32 v242, v242
	v_rcp_f32_e32 v243, v243
	v_fma_f32 v240, v240, v246, v247
	v_fma_f32 v241, v241, v246, v247
	v_fma_f32 v242, v242, v246, v247
	v_fma_f32 v243, v243, v246, v247
	v_cndmask_b32_e64 v28, v240, v28, s[98:99]
	v_cndmask_b32_e64 v29, v241, v29, s[98:99]
	v_cndmask_b32_e64 v26, v242, v26, s[98:99]
	v_cndmask_b32_e64 v27, v243, v27, s[98:99]
	v_cvt_pk_bf16_f32 v30, v24, v25
	v_cvt_pk_bf16_f32 v31, v22, v23
	v_cvt_pk_bf16_f32 v32, v28, v29
	v_cvt_pk_bf16_f32 v33, v26, v27
	ds_write_b128 v208, v[30:33] offset:80
	global_load_dwordx4 v[22:25], v[20:21], off offset:3168
	global_load_dwordx4 v[26:29], v[0:1], off offset:3168
	global_load_dwordx4 v[30:33], v[120:121], off
	global_load_dwordx4 v[34:37], v[120:121], off offset:16
	v_cmp_lt_i32_e64 s[6:7], 0, v207
	s_waitcnt vmcnt(3)
	v_cndmask_b32_e64 v2, v23, 0, vcc
	v_cndmask_b32_e64 v42, v22, 0, vcc
	v_cndmask_b32_e64 v25, v25, 0, vcc
	v_cndmask_b32_e64 v24, v24, 0, vcc
	s_waitcnt vmcnt(2)
	v_lshlrev_b32_e32 v38, 16, v26
	v_and_b32_e32 v39, 0xffff0000, v26
	v_lshlrev_b32_e32 v22, 16, v27
	v_and_b32_e32 v23, 0xffff0000, v27
	v_lshlrev_b32_e32 v40, 16, v28
	v_and_b32_e32 v41, 0xffff0000, v28
	v_lshlrev_b32_e32 v26, 16, v29
	v_and_b32_e32 v27, 0xffff0000, v29
	v_lshlrev_b32_e32 v28, 16, v42
	v_and_b32_e32 v29, 0xffff0000, v42
	v_lshlrev_b32_e32 v42, 16, v2
	v_and_b32_e32 v2, 0xffff0000, v2
	v_lshlrev_b32_e32 v44, 16, v24
	v_and_b32_e32 v43, 0xffff0000, v24
	v_lshlrev_b32_e32 v46, 16, v25
	v_and_b32_e32 v45, 0xffff0000, v25
	v_sub_f32_e32 v25, v29, v39
	v_sub_f32_e32 v24, v28, v38
	v_sub_f32_e32 v29, v2, v23
	v_sub_f32_e32 v28, v42, v22
	v_sub_f32_e32 v43, v43, v41
	v_sub_f32_e32 v42, v44, v40
	v_sub_f32_e32 v45, v45, v27
	v_sub_f32_e32 v44, v46, v26
	s_waitcnt vmcnt(1)
	v_pk_fma_f32 v[22:23], v[32:33], v[28:29], v[22:23]
	v_pk_fma_f32 v[24:25], v[30:31], v[24:25], v[38:39]
	s_waitcnt vmcnt(0)
; #define LAS __attribute__((address_space(3)))
; __device__ __forceinline__ unsigned pk2(float lo, float hi) { const f32x2c v = {lo, hi}; const bf16x2c b = __builtin_convertvector(v, bf16x2c); return __builtin_bit_cast(unsigned, b); }
; __device__ __forceinline__ float bflo(unsigned w) { return __uint_as_float(w << 16); }
; __device__ __forceinline__ float bfhi(unsigned w) { return __uint_as_float(w & 0xffff0000u); }
; __device__ __forceinline__ float fast_sigmoid(float x) { return __builtin_amdgcn_rcpf(1.f + __expf(-x)); }
; __device__ __forceinline__ f32x4 lerp4(const bf16_t* cur, const bf16_t* prv, bool first, const float* mu) {
;     const u32x2 a = *(const u32x2*)cur; u32x2 q = *(const u32x2*)prv; if (first) { q.x = 0u; q.y = 0u; }
;     const f32x4 m = *(const f32x4*)mu;
;     const f32x4 x = {bflo(a.x), bfhi(a.x), bflo(a.y), bfhi(a.y)}, y = {bflo(q.x), bfhi(q.x), bflo(q.y), bfhi(q.y)};
;     return x + (y - x) * m;
; }
; __device__ __forceinline__ void prep_rwkv_phase(const Params& p, LAS unsigned char* lds, int gw, int ngw, int wave, int lane) {
;     ...
;         for (int g8 = 0; g8 < 8; ++g8) {
;             const f32x4 x0 = lerp4(pr + g8 * 8, pp + g8 * 8, first, p.mu + 1536 + cq * 64 + g8 * 8);
;             const f32x4 x1 = lerp4(pr + g8 * 8 + 4, pp + g8 * 8 + 4, first, p.mu + 1536 + cq * 64 + g8 * 8 + 4);
;             float v[8] = {x0.x, x0.y, x0.z, x0.w, x1.x, x1.y, x1.z, x1.w};
; #pragma unroll
;             for (int e = 0; e < 8; ++e) { if (cq == 0) v[e] = 1.f - 2.f * __builtin_amdgcn_rcpf(__expf(2.f * v[e]) + 1.f); else if (cq >= 2) v[e] = fast_sigmoid(v[e]); }
;             u32x4 w; w.x = pk2(v[0], v[1]); w.y = pk2(v[2], v[3]); w.z = pk2(v[4], v[5]); w.w = pk2(v[6], v[7]);
;             *(LAS u32x4*)(act + tk * 264 + cq * 64 + g8 * 8) = w;
;         }
	v_pk_fma_f32 v[26:27], v[36:37], v[44:45], v[26:27]
	v_pk_fma_f32 v[28:29], v[34:35], v[42:43], v[40:41]
	v_mul_f32_e32 v240, v245, v24
	v_mul_f32_e32 v241, v245, v25
	v_mul_f32_e32 v242, v245, v22
	v_mul_f32_e32 v243, v245, v23
	v_exp_f32_e32 v240, v240
	v_exp_f32_e32 v241, v241
	v_exp_f32_e32 v242, v242
	v_exp_f32_e32 v243, v243
	v_add_f32_e32 v240, 1.0, v240
	v_add_f32_e32 v241, 1.0, v241
	v_add_f32_e32 v242, 1.0, v242
	v_add_f32_e32 v243, 1.0, v243
	v_rcp_f32_e32 v240, v240
	v_rcp_f32_e32 v241, v241
	v_rcp_f32_e32 v242, v242
	v_rcp_f32_e32 v243, v243
	v_fma_f32 v240, v240, v246, v247
	v_fma_f32 v241, v241, v246, v247
	v_fma_f32 v242, v242, v246, v247
	v_fma_f32 v243, v243, v246, v247
	v_cndmask_b32_e64 v24, v240, v24, s[98:99]
	v_cndmask_b32_e64 v25, v241, v25, s[98:99]
	v_cndmask_b32_e64 v22, v242, v22, s[98:99]
	v_cndmask_b32_e64 v23, v243, v23, s[98:99]
	v_mul_f32_e32 v240, v245, v28
	v_mul_f32_e32 v241, v245, v29
	v_mul_f32_e32 v242, v245, v26
	v_mul_f32_e32 v243, v245, v27
	v_exp_f32_e32 v240, v240
	v_exp_f32_e32 v241, v241
	v_exp_f32_e32 v242, v242
	v_exp_f32_e32 v243, v243
	v_add_f32_e32 v240, 1.0, v240
	v_add_f32_e32 v241, 1.0, v241
	v_add_f32_e32 v242, 1.0, v242
	v_add_f32_e32 v243, 1.0, v243
	v_rcp_f32_e32 v240, v240
	v_rcp_f32_e32 v241, v241
	v_rcp_f32_e32 v242, v242
	v_rcp_f32_e32 v243, v243
	v_fma_f32 v240, v240, v246, v247
	v_fma_f32 v241, v241, v246, v247
	v_fma_f32 v242, v242, v246, v247
	v_fma_f32 v243, v243, v246, v247
	v_cndmask_b32_e64 v28, v240, v28, s[98:99]
	v_cndmask_b32_e64 v29, v241, v29, s[98:99]
	v_cndmask_b32_e64 v26, v242, v26, s[98:99]
	v_cndmask_b32_e64 v27, v243, v27, s[98:99]
	v_cvt_pk_bf16_f32 v30, v24, v25
	v_cvt_pk_bf16_f32 v31, v22, v23
	v_cvt_pk_bf16_f32 v32, v28, v29
	v_cvt_pk_bf16_f32 v33, v26, v27
	ds_write_b128 v208, v[30:33] offset:96
	global_load_dwordx4 v[20:23], v[20:21], off offset:3184
	s_nop 0
	global_load_dwordx4 v[24:27], v[0:1], off offset:3184
	global_load_dwordx4 v[28:31], v[122:123], off
	global_load_dwordx4 v[32:35], v[122:123], off offset:16
	s_waitcnt vmcnt(3)
	v_cndmask_b32_e64 v2, v21, 0, vcc
	v_cndmask_b32_e64 v36, v20, 0, vcc
	v_cndmask_b32_e64 v37, v23, 0, vcc
	v_cndmask_b32_e64 v38, v22, 0, vcc
	s_waitcnt vmcnt(2)
	v_lshlrev_b32_e32 v20, 16, v24
	v_and_b32_e32 v21, 0xffff0000, v24
	v_lshlrev_b32_e32 v0, 16, v25
	v_and_b32_e32 v1, 0xffff0000, v25
	v_lshlrev_b32_e32 v24, 16, v26
	v_and_b32_e32 v25, 0xffff0000, v26
	v_lshlrev_b32_e32 v22, 16, v27
	v_and_b32_e32 v23, 0xffff0000, v27
	v_lshlrev_b32_e32 v26, 16, v36
	v_and_b32_e32 v27, 0xffff0000, v36
	v_lshlrev_b32_e32 v36, 16, v2
	v_and_b32_e32 v2, 0xffff0000, v2
	v_lshlrev_b32_e32 v40, 16, v38
	v_and_b32_e32 v38, 0xffff0000, v38
	v_lshlrev_b32_e32 v42, 16, v37
	v_and_b32_e32 v41, 0xffff0000, v37
	v_sub_f32_e32 v27, v27, v21
	v_sub_f32_e32 v26, v26, v20
	v_sub_f32_e32 v37, v2, v1
	v_sub_f32_e32 v36, v36, v0
	v_sub_f32_e32 v39, v38, v25
	v_sub_f32_e32 v38, v40, v24
	v_sub_f32_e32 v41, v41, v23
	v_sub_f32_e32 v40, v42, v22
	s_waitcnt vmcnt(1)
	v_pk_fma_f32 v[0:1], v[30:31], v[36:37], v[0:1]
	v_pk_fma_f32 v[20:21], v[28:29], v[26:27], v[20:21]
	s_waitcnt vmcnt(0)
	v_pk_fma_f32 v[22:23], v[34:35], v[40:41], v[22:23]
	v_pk_fma_f32 v[24:25], v[32:33], v[38:39], v[24:25]
	v_mul_f32_e32 v240, v245, v20
	v_mul_f32_e32 v241, v245, v21
	v_mul_f32_e32 v242, v245, v0
	v_mul_f32_e32 v243, v245, v1
	v_exp_f32_e32 v240, v240
	v_exp_f32_e32 v241, v241
	v_exp_f32_e32 v242, v242
	v_exp_f32_e32 v243, v243
	v_add_f32_e32 v240, 1.0, v240
	v_add_f32_e32 v241, 1.0, v241
	v_add_f32_e32 v242, 1.0, v242
	v_add_f32_e32 v243, 1.0, v243
	v_rcp_f32_e32 v240, v240
	v_rcp_f32_e32 v241, v241
	v_rcp_f32_e32 v242, v242
	v_rcp_f32_e32 v243, v243
	v_fma_f32 v240, v240, v246, v247
	v_fma_f32 v241, v241, v246, v247
	v_fma_f32 v242, v242, v246, v247
	v_fma_f32 v243, v243, v246, v247
	v_cndmask_b32_e64 v20, v240, v20, s[98:99]
	v_cndmask_b32_e64 v21, v241, v21, s[98:99]
	v_cndmask_b32_e64 v0, v242, v0, s[98:99]
	v_cndmask_b32_e64 v1, v243, v1, s[98:99]
	v_mul_f32_e32 v240, v245, v24
	v_mul_f32_e32 v241, v245, v25
	v_mul_f32_e32 v242, v245, v22
	v_mul_f32_e32 v243, v245, v23
	v_exp_f32_e32 v240, v240
	v_exp_f32_e32 v241, v241
	v_exp_f32_e32 v242, v242
	v_exp_f32_e32 v243, v243
	v_add_f32_e32 v240, 1.0, v240
	v_add_f32_e32 v241, 1.0, v241
	v_add_f32_e32 v242, 1.0, v242
	v_add_f32_e32 v243, 1.0, v243
	v_rcp_f32_e32 v240, v240
	v_rcp_f32_e32 v241, v241
	v_rcp_f32_e32 v242, v242
	v_rcp_f32_e32 v243, v243
	v_fma_f32 v240, v240, v246, v247
	v_fma_f32 v241, v241, v246, v247
	v_fma_f32 v242, v242, v246, v247
	v_fma_f32 v243, v243, v246, v247
	v_cndmask_b32_e64 v24, v240, v24, s[98:99]
	v_cndmask_b32_e64 v25, v241, v25, s[98:99]
	v_cndmask_b32_e64 v22, v242, v22, s[98:99]
	v_cndmask_b32_e64 v23, v243, v23, s[98:99]
	v_cvt_pk_bf16_f32 v26, v20, v21
	v_cvt_pk_bf16_f32 v27, v0, v1
	v_cvt_pk_bf16_f32 v28, v24, v25
	v_cvt_pk_bf16_f32 v29, v22, v23
	ds_write_b128 v208, v[26:29] offset:112

; __device__ __forceinline__ h16* chunk_base(const Params& p, int item) { return (h16*)(p.ws + WS_SC) + ((size_t)(item >> 7) * SEQ + (size_t)(item & 127) * 64) * 384; }
; #define lane (lane_now())
; __device__ __forceinline__ void chunk_load(const Params& p, int item, int tid, h16 (&raw)[48]) {
;     const h16* base = chunk_base(p, item) + (size_t)(8 * (tid >> 6)) * 384 + (tid & 63);
; #pragma unroll
;     for (int i = 0; i < 8; ++i)
; #pragma unroll
;         for (int vq = 0; vq < 6; ++vq) raw[i * 6 + vq] = base[(size_t)i * 384 + vq * 64];
; }
; __global__ void __launch_bounds__(512, 2) mega_fwd(Params p) {
;     ...
;     { const int lane7 = lane, tid7 = wave * 64 + lane7;
;       h16 raw[48]; if ((int)blockIdx.x < 32 * 128) chunk_load(p, (int)blockIdx.x, tid7, raw);
;       for (int it = blockIdx.x; it < 32 * 128; it += G) chunk_pre(p, lds, it, (it + G < 32 * 128) ? it + G : -1, tid7, wave, lane7, raw); }
.LBB0_920:
	s_add_u32 s6, s92, 0x13b00000
	s_addc_u32 s7, s93, 0
	s_cmpk_lt_i32 s82, 0x1000
	s_movk_i32 s53, 0x1000
	s_waitcnt lgkmcnt(0)
	s_barrier
	v_mbcnt_lo_u32_b32 v1, -1, 0
	v_mbcnt_hi_u32_b32 v1, -1, v1
	s_cbranch_scc0 .LBB0_945
	v_readlane_b32 s45, v244, 0
	s_lshr_b32 s100, s45, 6
	s_lshl_b32 s100, s100, 10
	s_and_b32 s101, s45, 63
	s_lshl_b32 s101, s101, 1
	s_or_b32 s100, s100, s101
	s_cmp_eq_u32 s94, 0x100
	s_cselect_b32 s45, s100, s45
	v_readlane_b32 s98, v244, 61
	s_cmp_eq_u32 s98, 0
	s_cbranch_scc1 .Lxq_keep
	v_readlane_b32 s100, v244, 0
	s_and_b32 s101, s100, 7
	s_lshr_b32 s100, s100, 3
	s_lshl_b32 s100, s100, 1
	s_and_b32 s98, s101, 1
	s_lshl_b32 s98, s98, 6
	s_add_i32 s100, s100, s98
	s_lshr_b32 s101, s101, 1
	s_lshl_b32 s101, s101, 10
	s_add_i32 s45, s100, s101
.Lxq_keep:
	s_ashr_i32 s0, s45, 7
	s_ashr_i32 s1, s0, 31
	s_lshl_b32 s4, s45, 6
	s_lshl_b64 s[0:1], s[0:1], 13
	s_and_b32 s4, s4, 0x1fc0
	s_or_b32 s4, s0, s4
	s_mulk_i32 s1, 0x300
	s_mul_hi_u32 s5, s4, 0x300
	s_add_i32 s5, s5, s1
	s_mulk_i32 s4, 0x300
	v_add_u32_e32 v0, s86, v1
	s_add_u32 s4, s6, s4
	s_addc_u32 s5, s7, s5
	v_ashrrev_i32_e32 v2, 3, v0
	s_movk_i32 s0, 0x300
	s_waitcnt vmcnt(3)
	v_and_b32_e32 v4, -8, v2
	v_mov_b64_e32 v[2:3], s[4:5]
	v_and_b32_e32 v5, 63, v1
	v_mad_i64_i32 v[2:3], s[4:5], v4, s0, v[2:3]
	v_lshlrev_b32_e32 v20, 1, v5
	v_mov_b32_e32 v21, 0
	v_lshl_add_u64 v[2:3], v[2:3], 0, v[20:21]
	global_load_ushort v40, v[2:3], off
	global_load_ushort v41, v[2:3], off offset:128
	global_load_ushort v42, v[2:3], off offset:256
	global_load_ushort v43, v[2:3], off offset:384
	global_load_ushort v44, v[2:3], off offset:512
	global_load_ushort v45, v[2:3], off offset:640
	global_load_ushort v46, v[2:3], off offset:768
	global_load_ushort v47, v[2:3], off offset:896
	global_load_ushort v48, v[2:3], off offset:1024
	global_load_ushort v49, v[2:3], off offset:1152
	global_load_ushort v50, v[2:3], off offset:1280
	global_load_ushort v51, v[2:3], off offset:1408
	global_load_ushort v52, v[2:3], off offset:1536
	global_load_ushort v53, v[2:3], off offset:1664
	global_load_ushort v54, v[2:3], off offset:1792
	global_load_ushort v55, v[2:3], off offset:1920
	global_load_ushort v56, v[2:3], off offset:2048
	global_load_ushort v57, v[2:3], off offset:2176
	global_load_ushort v58, v[2:3], off offset:2304
	global_load_ushort v59, v[2:3], off offset:2432
	global_load_ushort v60, v[2:3], off offset:2560
	global_load_ushort v61, v[2:3], off offset:2688
	global_load_ushort v62, v[2:3], off offset:2816
	global_load_ushort v64, v[2:3], off offset:2944
	global_load_ushort v66, v[2:3], off offset:3072
	global_load_ushort v67, v[2:3], off offset:3200
	global_load_ushort v68, v[2:3], off offset:3328
	global_load_ushort v69, v[2:3], off offset:3456
	global_load_ushort v70, v[2:3], off offset:3584
	global_load_ushort v71, v[2:3], off offset:3712
	global_load_ushort v72, v[2:3], off offset:3840
	global_load_ushort v73, v[2:3], off offset:3968
	v_add_co_u32_e32 v2, vcc, s53, v2
	v_and_b32_e32 v6, 15, v1
	s_nop 0
	v_addc_co_u32_e32 v3, vcc, 0, v3, vcc
	global_load_ushort v75, v[2:3], off
	global_load_ushort v76, v[2:3], off offset:128
	global_load_ushort v78, v[2:3], off offset:256
	global_load_ushort v80, v[2:3], off offset:384
	global_load_ushort v81, v[2:3], off offset:512
	global_load_ushort v82, v[2:3], off offset:640
	global_load_ushort v83, v[2:3], off offset:768
	global_load_ushort v84, v[2:3], off offset:896
	global_load_ushort v85, v[2:3], off offset:1024
	global_load_ushort v86, v[2:3], off offset:1152
	global_load_ushort v87, v[2:3], off offset:1280
	global_load_ushort v88, v[2:3], off offset:1408
	global_load_ushort v89, v[2:3], off offset:1536
	global_load_ushort v90, v[2:3], off offset:1664
	global_load_ushort v92, v[2:3], off offset:1792
	global_load_ushort v93, v[2:3], off offset:1920
	v_ashrrev_i32_e32 v2, 6, v0
	v_cmp_lt_i32_e64 s[4:5], 1, v2
	v_cmp_eq_u32_e64 s[46:47], 0, v6
	v_cmp_lt_i32_e64 s[82:83], 0, v2
	v_writelane_b32 v244, s4, 33
	v_cndmask_b32_e64 v101, 0, 1.0, s[46:47]
	v_cmp_eq_u32_e64 s[46:47], 1, v6
	v_writelane_b32 v244, s5, 34
	v_cmp_lt_i32_e64 s[4:5], 2, v2
	v_cndmask_b32_e64 v103, 0, 1.0, s[46:47]
	v_cmp_eq_u32_e64 s[46:47], 2, v6
	v_writelane_b32 v244, s4, 35
	s_add_i32 s8, 0, 0x1a800
	v_cndmask_b32_e64 v104, 0, 1.0, s[46:47]
	v_writelane_b32 v244, s5, 36
	v_cmp_lt_i32_e64 s[4:5], 3, v2
	v_cmp_eq_u32_e64 s[46:47], 3, v6
	v_ashrrev_i32_e32 v7, 4, v1
	v_writelane_b32 v244, s4, 37
	v_cndmask_b32_e64 v105, 0, 1.0, s[46:47]
	v_cmp_eq_u32_e64 s[46:47], 4, v6
	v_writelane_b32 v244, s5, 38
	v_cmp_lt_i32_e64 s[4:5], 4, v2
	v_cndmask_b32_e64 v106, 0, 1.0, s[46:47]
	v_cmp_eq_u32_e64 s[46:47], 5, v6
	v_writelane_b32 v244, s4, 39
	s_movk_i32 s79, 0x90
	v_cndmask_b32_e64 v107, 0, 1.0, s[46:47]
	v_writelane_b32 v244, s5, 40
	v_cmp_lt_i32_e64 s[4:5], 5, v2
	v_cmp_eq_u32_e64 s[46:47], 6, v6
	s_waitcnt vmcnt(50)
; __device__ __forceinline__ void chunk_pre(const Params& p, LAS unsigned char* lds, int item, int next_item, int tid, int wave, int lane, h16 (&raw)[48]) {
;     h16* base = chunk_base(p, item);
;     LAS bf16_t* At = (LAS bf16_t*)lds; LAS bf16_t* Bt = At + 64 * MS; LAS bf16_t* Kt = Bt + 64 * MS; LAS bf16_t* Rt = Kt + 64 * MS;
;     LAS bf16_t* BhT = Rt + 64 * MS; LAS bf16_t* KhT = BhT + 64 * MS; LAS bf16_t* VT = KhT + 64 * MS;
;     LAS bf16_t* Mak = VT + 64 * MS; LAS bf16_t* Mrb = Mak + 64 * MS; LAS bf16_t* Mrk = Mrb + 64 * MS;
;     LAS bf16_t* AbT = Bt; LAS bf16_t* P1T = Kt;
;     LAS float* Mab = (LAS float*)(lds + 92160); LAS float* GT = (LAS float*)(lds + 141312);
;     LAS bf16_t* AtT = (LAS bf16_t*)(lds + 108544); LAS bf16_t* RH2T = (LAS bf16_t*)(lds + 117760);
;     LAS float* TD = (LAS float*)(lds + 126976); LAS float* Toff = (LAS float*)(lds + 131072); LAS float* Wf = (LAS float*)(lds + 137216);
;     LAS bf16_t* Tb = At;
;     const int fr = lane & 15, fq = lane >> 4;
;     {
;         const int g = tid >> 6, k = tid & 63;
;         float wv[8], lp[8];
; #pragma unroll
;         for (int i = 0; i < 8; ++i) wv[i] = (float)raw[i * 6 + 2];
;         lp[0] = wv[0];
; #pragma unroll
;         for (int i = 1; i < 8; ++i) lp[i] = lp[i - 1] * wv[i];
;         GT[g * 64 + k] = lp[7];
;         BAR_LDS();
;         float bs = 1.f, WL = 1.f;
; #pragma unroll
;         for (int q = 0; q < 8; ++q) { const float gq = GT[q * 64 + k]; if (q < g) bs *= gq; WL *= gq; }
;         float bhv[8], khv[8], vtv[8], atv[8];
; #pragma unroll
;         for (int i = 0; i < 8; ++i) {
;             const int t = 8 * g + i;
;             const float kk = (float)raw[i * 6 + 0], wr = (float)raw[i * 6 + 1], bb = (float)raw[i * 6 + 3], kx = (float)raw[i * 6 + 4], vv = (float)raw[i * 6 + 5];
;             const float Wt = bs * lp[i], Wp = (i == 0) ? bs : bs * lp[i - 1], iW = 1.f / Wt;
;             atv[i] = -kk * Wp; At[t * MS + k] = (bf16_t)(pk2(-kk * Wp, 0.f) & 0xffffu); Rt[t * MS + k] = (bf16_t)(pk2(wr * Wp, 0.f) & 0xffffu);
;             Bt[t * MS + k] = (bf16_t)(pk2(bb * iW, 0.f) & 0xffffu); Kt[t * MS + k] = (bf16_t)(pk2(kx * iW, 0.f) & 0xffffu);
;             bhv[i] = bb * iW * WL; khv[i] = kx * iW * WL; vtv[i] = vv;
;         }
;         *(LAS u32x4*)(BhT + k * MS + 8 * g) = (u32x4){pk2(bhv[0], bhv[1]), pk2(bhv[2], bhv[3]), pk2(bhv[4], bhv[5]), pk2(bhv[6], bhv[7])};
	v_mov_b32_e32 v10, 0x900
	v_writelane_b32 v244, s4, 41
	v_cndmask_b32_e64 v108, 0, 1.0, s[46:47]
	v_cmp_eq_u32_e64 s[46:47], 7, v6
	v_writelane_b32 v244, s5, 42
	v_cmp_lt_i32_e64 s[4:5], 6, v2
	v_cndmask_b32_e64 v109, 0, 1.0, s[46:47]
	v_cmp_eq_u32_e64 s[46:47], 8, v6
	v_writelane_b32 v244, s4, 43
	v_lshlrev_b32_e32 v100, 1, v6
	v_cndmask_b32_e64 v110, 0, 1.0, s[46:47]
	v_writelane_b32 v244, s5, 44
	v_cmp_lt_i32_e64 s[4:5], 7, v2
	v_cmp_eq_u32_e64 s[46:47], 9, v6
	s_add_i32 s1, 0, 0x22800
	v_writelane_b32 v244, s4, 45
	v_cndmask_b32_e64 v111, 0, 1.0, s[46:47]
	v_cmp_eq_u32_e64 s[46:47], 10, v6
	v_writelane_b32 v244, s5, 46
	s_movk_i32 s4, 0x240
	v_mul_lo_u32 v3, v2, s4
	v_or_b32_e32 v3, v3, v5
	v_lshl_add_u32 v74, v3, 1, 0
	v_mul_u32_u24_e32 v3, 0x48, v5
	v_lshlrev_b32_e32 v3, 1, v3
	v_lshlrev_b32_e32 v2, 4, v2
	v_add3_u32 v77, 0, v3, v2
	v_add3_u32 v79, s8, v3, v2
	v_mov_b64_e32 v[2:3], s[6:7]
	v_mad_i64_i32 v[2:3], s[4:5], v4, s0, v[2:3]
	v_readlane_b32 s4, v244, 14
	s_lshl_b32 s4, s4, 3
	s_and_b32 s4, s4, 0x1ffffff0
	v_or_b32_e32 v4, s4, v6
	v_readlane_b32 s4, v244, 20
	v_cndmask_b32_e64 v112, 0, 1.0, s[46:47]
	v_cmp_eq_u32_e64 s[46:47], 11, v6
	v_lshl_add_u64 v[22:23], v[2:3], 0, v[20:21]
	s_and_b32 s4, s4, 32
	v_and_b32_e32 v20, -16, v0
	v_cndmask_b32_e64 v113, 0, 1.0, s[46:47]
	v_cmp_eq_u32_e64 s[46:47], 12, v6
	v_mul_lo_u32 v2, v4, s79
	v_or_b32_e32 v3, s4, v6
	v_lshl_add_u32 v24, v7, 2, s4
	s_add_i32 s5, 0, 0x12000
	v_lshlrev_b32_e32 v25, 2, v20
	v_lshlrev_b32_e32 v26, 1, v20
	v_mul_lo_u32 v38, v20, s79
	v_lshlrev_b32_e32 v20, 8, v20
	v_cndmask_b32_e64 v114, 0, 1.0, s[46:47]
	v_cmp_eq_u32_e64 s[46:47], 13, v6
	v_mul_u32_u24_e32 v9, 0x90, v3
	v_mad_u32_u24 v10, v3, s79, v10
	v_lshlrev_b32_e32 v3, 8, v4
	s_add_i32 s18, 0, 0x16800
	s_waitcnt vmcnt(49)
	v_lshlrev_b32_e32 v15, 2, v24
	s_waitcnt vmcnt(48)
; __device__ __forceinline__ void chunk_pre(const Params& p, LAS unsigned char* lds, int item, int next_item, int tid, int wave, int lane, h16 (&raw)[48]) {
;     h16* base = chunk_base(p, item);
;     LAS bf16_t* At = (LAS bf16_t*)lds; LAS bf16_t* Bt = At + 64 * MS; LAS bf16_t* Kt = Bt + 64 * MS; LAS bf16_t* Rt = Kt + 64 * MS;
;     LAS bf16_t* BhT = Rt + 64 * MS; LAS bf16_t* KhT = BhT + 64 * MS; LAS bf16_t* VT = KhT + 64 * MS;
;     LAS bf16_t* Mak = VT + 64 * MS; LAS bf16_t* Mrb = Mak + 64 * MS; LAS bf16_t* Mrk = Mrb + 64 * MS;
;     LAS bf16_t* AbT = Bt; LAS bf16_t* P1T = Kt;
;     LAS float* Mab = (LAS float*)(lds + 92160); LAS float* GT = (LAS float*)(lds + 141312);
;     LAS bf16_t* AtT = (LAS bf16_t*)(lds + 108544); LAS bf16_t* RH2T = (LAS bf16_t*)(lds + 117760);
;     LAS float* TD = (LAS float*)(lds + 126976); LAS float* Toff = (LAS float*)(lds + 131072); LAS float* Wf = (LAS float*)(lds + 137216);
;     LAS bf16_t* Tb = At;
;     const int fr = lane & 15, fq = lane >> 4;
;     {
;         const int g = tid >> 6, k = tid & 63;
;     ...
;     const int a0 = 16 * (wave >> 1), ar = a0 + fr;
;     {
;         f32x4 acc[2];
; #pragma unroll
;         for (int which = 0; which < 4; ++which) {
;             acc[0] = (f32x4){0.f, 0.f, 0.f, 0.f}; acc[1] = acc[0];
;             mm64((which & 1) ? Kt : Bt, (which & 2) ? Rt : At, acc, wave, fr, fq);
; #pragma unroll
;             for (int nt = 0; nt < 2; ++nt) { const int s0 = 32 * (wave & 1) + 16 * nt + 4 * fq; f32x4 v = acc[nt];
; #pragma unroll
;                 for (int jj = 0; jj < 4; ++jj) { const bool keep = (which & 2) ? (s0 + jj <= ar) : (s0 + jj < ar); if (!keep) v[jj] = 0.f; }
;                 if (which == 0) *(LAS f32x4*)(Mab + ar * 64 + s0) = v;
;                 else st_bf4(((which == 1) ? Mak : (which == 2) ? Mrb : Mrk) + ar * MS + s0, v); }
;         }
;     }
;     BAR_LDS();
;     {
;         f32x4 acc[2]; acc[0] = (f32x4){0.f, 0.f, 0.f, 0.f}; acc[1] = acc[0];
;         mm64(Mak, VT, acc, wave, fr, fq);
; #pragma unroll
;         for (int nt = 0; nt < 2; ++nt) st_bf4(RH2T + ar * MS + 32 * (wave & 1) + 16 * nt + 4 * fq, acc[nt]);
;     }
;     for (int e = tid; e < 6 * 256; e += 512) { const int ub = e >> 8, i = (e >> 4) & 15, j = e & 15;
;         const int r = ub < 3 ? 0 : ub < 5 ? 1 : 2, c = ub < 3 ? ub + 1 : ub < 5 ? ub - 1 : 3; Tb[(16 * r + i) * MS + 16 * c + j] = 0; }
	v_add_u32_e32 v19, s5, v2
	s_add_i32 s5, 0, 0x14400
	v_add3_u32 v36, 0, v26, v100
	v_lshlrev_b32_e32 v26, 6, v0
	v_or_b32_e32 v39, 0x100, v20
	v_or_b32_e32 v144, 0x200, v20
	v_or_b32_e32 v145, 0x300, v20
	v_or_b32_e32 v146, 0x400, v20
	v_or_b32_e32 v147, 0x500, v20
	v_or_b32_e32 v148, 0x600, v20
	v_or_b32_e32 v149, 0x700, v20
	v_or_b32_e32 v150, 0x800, v20
	v_or_b32_e32 v151, 0x900, v20
	v_or_b32_e32 v152, 0xa00, v20
	v_or_b32_e32 v153, 0xb00, v20
	v_or_b32_e32 v154, 0xc00, v20
	v_or_b32_e32 v155, 0xd00, v20
	v_cndmask_b32_e64 v115, 0, 1.0, s[46:47]
	v_or_b32_e32 v156, 0xe00, v20
	v_cmp_eq_u32_e64 s[46:47], 14, v6
	v_or_b32_e32 v20, 15, v0
	v_lshl_add_u32 v65, v5, 2, s1
	v_lshlrev_b32_e32 v5, 3, v7
	v_add_u32_e32 v7, 0, v2
	v_add3_u32 v94, s18, v3, v15
	v_lshlrev_b32_e32 v3, 1, v24
	v_add_u32_e32 v28, s5, v2
	s_add_i32 s5, 0, 0x1cc00
	v_lshlrev_b32_e32 v98, 2, v6
	v_and_b32_e32 v37, 0xfffffc00, v26
	v_cndmask_b32_e64 v116, 0, 1.0, s[46:47]
	v_lshlrev_b32_e32 v157, 8, v20
	v_cmp_eq_u32_e64 s[46:47], 15, v6
	v_mul_lo_u32 v6, v20, s79
	v_ashrrev_i32_e32 v20, 8, v0
	v_ashrrev_i32_e32 v26, 4, v0
	v_add_u32_e32 v95, v7, v3
	v_add_u32_e32 v96, v19, v3
	v_add_u32_e32 v97, v28, v3
	v_add_u32_e32 v3, s5, v2
	s_movk_i32 s5, 0x600
	v_and_b32_e32 v27, 15, v26
	v_add_u32_e32 v29, 2, v20
	v_cmp_gt_i32_e64 s[10:11], s5, v0
	v_lshl_or_b32 v30, v29, 4, v27
	v_lshl_add_u32 v31, v30, 8, s18
	v_writelane_b32 v244, s10, 47
	v_lshlrev_b32_e32 v32, 6, v20
	v_cvt_pk_bf16_f32 v102, v101, s0
	v_writelane_b32 v244, s11, 48
	v_cmp_gt_i32_e64 s[10:11], 64, v0
	v_cndmask_b32_e64 v117, 0, 1.0, s[46:47]
	v_cmp_gt_i32_e64 s[46:47], s0, v0
	s_add_i32 s42, 0, 0x21800
	v_add_u32_e32 v119, v31, v32
	v_and_b32_e32 v31, 0x3fffff00, v0
	s_add_i32 s43, 0, 0x20000
	s_add_i32 s0, 0, 0x20c00
	v_lshlrev_b32_e32 v8, 2, v0
	v_writelane_b32 v244, s10, 49
	v_add_u32_e32 v118, s42, v98
	v_lshlrev_b32_e32 v31, 2, v31
	v_add_u32_e32 v121, s43, v98
	v_add_u32_e32 v128, s0, v98
	s_add_i32 s0, 0, 0x1fc00
	v_add_u32_e32 v63, s1, v8
	v_writelane_b32 v244, s11, 50
	s_add_i32 s19, 0, 0x1f000
	v_add_u32_e32 v122, v121, v31
	v_lshlrev_b32_e32 v27, 6, v27
	v_add_u32_e32 v123, v118, v31
	v_lshlrev_b32_e32 v29, 10, v29
	v_add_u32_e32 v130, s0, v25
	v_lshl_add_u32 v136, v4, 2, s1
	v_cmp_eq_u32_e64 s[0:1], v24, v4
	v_and_b32_e32 v1, -16, v1
	v_or_b32_e32 v12, 1, v24
	v_add_u32_e32 v124, v123, v27
	v_add3_u32 v125, s19, v29, v27
	v_add_u32_e32 v126, v122, v27
	v_mul_lo_u32 v27, v30, s79
	v_writelane_b32 v244, s0, 51
	v_add_u32_e32 v91, v7, v1
	v_add_u32_e32 v11, 0, v1
	v_add_u32_e32 v27, 0, v27
	v_lshlrev_b32_e32 v20, 5, v20
	v_add3_u32 v132, s8, v2, v1
	v_add_u32_e32 v133, v3, v1
	v_add_u32_e32 v134, v19, v1
	v_mul_lo_u32 v2, v4, 6
	v_add_u32_e32 v135, v28, v1
	v_writelane_b32 v244, s1, 52
	v_cmp_eq_u32_e64 s[0:1], v12, v4
	v_max_i32_e32 v1, 0x400, v0
	v_or_b32_e32 v13, 2, v24
	s_lshl_b32 s4, s4, 1
	v_add3_u32 v127, v27, v20, v100
	v_add_u32_e32 v20, 2, v2
	v_writelane_b32 v244, s0, 53
	v_sub_u32_e32 v1, v1, v0
	v_add_u32_e32 v34, s4, v3
	v_add_u32_e32 v99, s19, v98
	v_lshlrev_b32_e32 v162, 8, v26
	v_add_u32_e32 v129, s42, v8
	v_mul_lo_u32 v8, v26, s79
	v_lshlrev_b64 v[26:27], 7, v[20:21]
	v_add_u32_e32 v20, 3, v2
	v_mov_b32_e32 v3, v21
	v_writelane_b32 v244, s1, 54
	v_cmp_eq_u32_e64 s[0:1], v13, v4
	v_add_u32_e32 v1, 0x1ff, v1
	v_or_b32_e32 v14, 3, v24
	v_add_u32_e32 v15, 16, v24
	v_add_u32_e32 v16, 17, v24
	v_add_u32_e32 v17, 18, v24
	v_add_u32_e32 v18, 19, v24
	s_movk_i32 s5, 0x100
	v_add_u32_e32 v120, v99, v31
	v_lshlrev_b64 v[28:29], 7, v[20:21]
	v_lshlrev_b64 v[30:31], 7, v[2:3]
	v_writelane_b32 v244, s0, 55
	v_or_b32_e32 v20, 1, v2
	v_lshrrev_b32_e32 v2, 9, v1
	s_movk_i32 s8, 0x5ff
	v_cmp_lt_i32_e64 s[20:21], v24, v4
	v_cmp_lt_i32_e32 vcc, v12, v4
	v_cmp_lt_i32_e64 s[70:71], v13, v4
	v_cmp_lt_i32_e64 s[22:23], v14, v4
	v_cmp_lt_i32_e64 s[24:25], v15, v4
	v_cmp_lt_i32_e64 s[76:77], v16, v4
	v_cmp_lt_i32_e64 s[74:75], v17, v4
	v_cmp_lt_i32_e64 s[26:27], v18, v4
	v_cmp_gt_i32_e64 s[28:29], v24, v4
	v_cmp_gt_i32_e64 s[30:31], v13, v4
	v_cmp_gt_i32_e64 s[34:35], v14, v4
	v_cmp_gt_i32_e64 s[36:37], v15, v4
	v_cmp_gt_i32_e64 s[38:39], v17, v4
	v_cmp_gt_i32_e64 s[40:41], v18, v4
	v_cmp_gt_i32_e64 s[48:49], s5, v0
	v_add_u32_e32 v7, s4, v7
	v_writelane_b32 v244, s1, 56
	v_cmp_eq_u32_e64 s[56:57], v14, v4
	v_cmp_eq_u32_e64 s[88:89], v15, v4
	v_cmp_eq_u32_e64 s[4:5], v16, v4
	v_cmp_eq_u32_e64 s[0:1], v17, v4
	v_cmp_eq_u32_e64 s[68:69], v18, v4
	v_add_u32_e32 v4, 1, v2
	v_cmp_lt_u32_e64 s[10:11], s8, v1
	v_and_b32_e32 v137, 0xfffffc, v4
	v_add_u32_e32 v35, s18, v25
	v_writelane_b32 v244, s10, 57
	s_or_b64 s[70:71], s[22:23], s[70:71]
	s_or_b64 s[74:75], s[26:27], s[74:75]
	v_writelane_b32 v244, s11, 58
	v_cmp_ne_u32_e64 s[10:11], v4, v137
	s_mov_b32 s9, 0
	v_add3_u32 v131, 0, v8, v100
	v_ashrrev_i32_e32 v25, 31, v24
	v_lshlrev_b64 v[32:33], 7, v[20:21]
	v_lshl_add_u32 v138, v137, 9, v0
	v_add_u32_e32 v3, 0x600, v0
	v_add_u32_e32 v2, 0x400, v0
	v_add_u32_e32 v1, 0x200, v0
	v_writelane_b32 v244, s10, 59
	v_add_u32_e32 v139, v11, v10
	v_add_u32_e32 v140, v34, v5
	v_add_u32_e32 v141, v99, v37
	v_add_u32_e32 v142, v36, v38
	v_add_u32_e32 v143, v35, v39
	v_add_u32_e32 v144, v35, v144
	v_add_u32_e32 v145, v35, v145
	v_add_u32_e32 v146, v35, v146
	v_add_u32_e32 v147, v35, v147
	v_add_u32_e32 v148, v35, v148
	v_add_u32_e32 v149, v35, v149
	v_add_u32_e32 v150, v35, v150
	v_add_u32_e32 v151, v35, v151
	v_add_u32_e32 v152, v35, v152
	v_add_u32_e32 v153, v35, v153
	v_add_u32_e32 v154, v35, v154
	v_add_u32_e32 v155, v35, v155
	v_add_u32_e32 v156, v35, v156
	v_add_u32_e32 v157, v35, v157
	v_add_u32_e32 v158, v36, v6
	s_movk_i32 s44, 0xff
	v_add_u32_e32 v159, v7, v5
	v_mov_b32_e32 v160, 0x300
	v_add_u32_e32 v161, v11, v9
	s_or_b64 s[72:73], s[70:71], vcc
	s_or_b64 s[76:77], s[74:75], s[76:77]
	v_add_u32_e32 v162, s18, v162
	v_writelane_b32 v244, s11, 60
	s_mov_b64 s[100:101], vcc
	v_cmp_gt_u32_e32 vcc, 0xc0, v0
	s_mov_b64 s[98:99], vcc
	v_lshrrev_b32_e32 v213, 1, v0
	v_and_b32_e32 v212, 1, v0
	v_lshrrev_b32_e32 v216, 4, v213
	v_and_b32_e32 v213, 15, v213
	v_cmp_lt_u32_e32 vcc, 2, v216
	s_nop 1
	v_cndmask_b32_e64 v217, 0, 1, vcc
	v_cmp_lt_u32_e32 vcc, 4, v216
	s_nop 1
	v_cndmask_b32_e64 v218, 0, 1, vcc
	v_add_u32_e32 v219, v217, v218
	v_lshl_add_u32 v213, v219, 4, v213
	v_add_u32_e32 v216, 1, v216
	v_lshlrev_b32_e32 v217, 1, v217
	v_sub_u32_e32 v216, v216, v217
	v_sub_u32_e32 v216, v216, v218
	v_lshlrev_b32_e32 v216, 5, v216
	v_lshl_add_u32 v212, v212, 4, v216
	v_mov_b32_e32 v217, 0x90
	v_mad_u32_u24 v212, v213, v217, v212
	v_mov_b32_e32 v214, 0
	v_mov_b32_e32 v215, 0
	s_mov_b64 vcc, s[100:101]
	s_branch .LBB0_923
